# v54 plus split-phase P3->P5 barrier for the latent-unit workgroups too: arrive, intra-chunk loop, wait right before the first prefix-state read; nobody polls at the barrier site
# speedup vs baseline: 1.0108x; 1.0108x over previous
.Lgb4_3_follow:
	s_branch .LBB0_360
	v_mov_b32_e32 v2, 3
	s_mov_b32 s99, 0

.LBB0_372:
	s_barrier
	s_waitcnt vmcnt(3)
	ds_write_b128 v136, v[98:101]
	s_waitcnt vmcnt(2)
	ds_write_b128 v136, v[102:105] offset:17408
	s_waitcnt vmcnt(1)
	ds_write_b128 v134, v[106:109]
	s_waitcnt vmcnt(0)
	ds_write_b128 v134, v[110:113] offset:17408
	v_add_u32_e32 v98, s19, v160
	v_add_u32_e32 v106, s19, v159
	v_mad_i64_i32 v[102:103], s[0:1], v98, s5, v[138:139]
	v_mad_i64_i32 v[110:111], s[0:1], v106, s5, v[138:139]
	s_waitcnt lgkmcnt(0)
	s_barrier
	global_load_dwordx4 v[98:101], v[102:103], off offset:1024
	s_nop 0
	global_load_dwordx4 v[102:105], v[102:103], off offset:2048
	s_nop 0
	global_load_dwordx4 v[106:109], v[110:111], off offset:1024
	s_nop 0
	global_load_dwordx4 v[110:113], v[110:111], off offset:2048
	ds_read_b128 v[114:117], v157
	ds_read_b128 v[118:121], v157 offset:64
	ds_read_b128 v[122:125], v157 offset:128
	ds_read_b128 v[126:129], v157 offset:192
	v_add_u32_e32 v162, s19, v158
	v_add_co_u32_e32 v130, vcc, 1, v162
	v_cvt_f32_i32_e32 v165, v162
	s_waitcnt lgkmcnt(3)
	v_mfma_f32_16x16x32_bf16 v[130:133], v[114:117], v[34:37], 0
	v_cvt_f32_i32_e32 v164, v161
	v_add_u32_e32 v163, -16, v162
	v_mul_f32_e32 v165, v142, v165
	v_mfma_f32_16x16x32_bf16 v[114:117], v[114:117], v[26:29], 0
	v_mul_f32_e32 v164, v144, v164
	v_exp_f32_e32 v165, v165
	v_exp_f32_e32 v164, v164
	s_waitcnt lgkmcnt(2)
	v_mfma_f32_16x16x32_bf16 v[130:133], v[118:121], v[30:33], v[130:133]
	v_cmp_gt_i32_e64 s[8:9], 0, v161
	v_mul_f32_e32 v167, v154, v165
	v_cmp_lt_i32_e64 s[6:7], 0, v161
	v_mfma_f32_16x16x32_bf16 v[114:117], v[118:121], v[22:25], v[114:117]
	v_add_u32_e32 v118, 16, v161
	v_cvt_f32_i32_e32 v119, v163
	v_cvt_f32_i32_e32 v118, v118
	s_waitcnt lgkmcnt(1)
	v_mfma_f32_16x16x32_bf16 v[114:117], v[122:125], v[6:9], v[114:117]
	v_mul_f32_e32 v166, v153, v164
	v_mul_f32_e32 v119, v142, v119
	v_cndmask_b32_e64 v167, 2.0, v167, s[8:9]
	v_mul_f32_e32 v168, v152, v165
	v_mul_f32_e32 v118, v144, v118
	v_exp_f32_e32 v119, v119
	v_cndmask_b32_e64 v166, v167, v166, s[6:7]
	v_cmp_lt_i32_e64 s[6:7], 1, v161
	v_mul_f32_e32 v167, v151, v164
	v_cndmask_b32_e64 v168, v168, 2.0, vcc
	v_exp_f32_e32 v118, v118
	v_cndmask_b32_e64 v167, v168, v167, s[6:7]
	v_mul_f32_e32 v169, v150, v165
	v_cmp_ne_u32_e64 s[6:7], -2, v162
	v_mfma_f32_16x16x32_bf16 v[130:133], v[122:125], v[14:17], v[130:133]
	v_cmp_lt_i32_e32 vcc, 2, v161
	v_mul_f32_e32 v168, v149, v164
	v_cndmask_b32_e64 v169, 2.0, v169, s[6:7]
	v_mul_f32_e32 v165, v146, v165
	v_cmp_ne_u32_e64 s[6:7], -3, v162
	s_waitcnt lgkmcnt(0)
	v_mfma_f32_16x16x32_bf16 v[114:117], v[126:129], v[2:5], v[114:117]
	v_cndmask_b32_e32 v168, v169, v168, vcc
	v_cmp_lt_i32_e32 vcc, 3, v161
	v_mul_f32_e32 v164, v148, v164
	v_cndmask_b32_e64 v165, 2.0, v165, s[6:7]
	v_mul_f32_e32 v121, v154, v119
	v_cmp_ne_u32_e64 s[6:7], 0, v163
	v_cndmask_b32_e32 v164, v165, v164, vcc
	v_cmp_lt_i32_e32 vcc, -16, v161
	v_mul_f32_e32 v120, v153, v118
	v_cndmask_b32_e64 v121, 2.0, v121, s[6:7]
	v_cndmask_b32_e32 v120, v121, v120, vcc
	v_mul_f32_e32 v121, v152, v119
	v_cmp_ne_u32_e64 s[6:7], 15, v162
	v_mfma_f32_16x16x32_bf16 v[130:133], v[126:129], v[10:13], v[130:133]
	v_mul_f32_e32 v114, v120, v114
	v_cmp_lt_i32_e32 vcc, -15, v161
	v_mul_f32_e32 v120, v151, v118
	v_cndmask_b32_e64 v121, 2.0, v121, s[6:7]
	v_cndmask_b32_e32 v120, v121, v120, vcc
	v_mul_f32_e32 v121, v150, v119
	v_cmp_ne_u32_e64 s[6:7], 14, v162
	v_mul_f32_e32 v115, v120, v115
	v_cmp_lt_i32_e32 vcc, -14, v161
	v_mul_f32_e32 v120, v149, v118
	v_cndmask_b32_e64 v121, 2.0, v121, s[6:7]
	v_mul_f32_e32 v119, v146, v119
	v_cmp_ne_u32_e64 s[6:7], 13, v162
	v_cndmask_b32_e32 v120, v121, v120, vcc
	v_cmp_lt_i32_e32 vcc, -13, v161
	v_mul_f32_e32 v118, v148, v118
	v_cndmask_b32_e64 v119, 2.0, v119, s[6:7]
	v_mul_f32_e32 v130, v166, v130
	v_mul_f32_e32 v131, v167, v131
	v_cndmask_b32_e32 v118, v119, v118, vcc
	v_mul_f32_e32 v132, v168, v132
	v_mul_f32_e32 v133, v164, v133
	v_cvt_pk_bf16_f32 v130, v130, v131
	v_cvt_pk_bf16_f32 v131, v132, v133
	ds_write_b64 v156, v[130:131] offset:53248
	v_mul_f32_e32 v116, v120, v116
	v_mul_f32_e32 v117, v118, v117
	v_cvt_pk_bf16_f32 v114, v114, v115
	v_cvt_pk_bf16_f32 v115, v116, v117
	ds_write_b64 v156, v[114:115] offset:55552
	ds_read_b128 v[114:117], v157 offset:4352
	ds_read_b128 v[118:121], v157 offset:4416
	ds_read_b128 v[122:125], v157 offset:4480
	ds_read_b128 v[126:129], v157 offset:4544
	s_waitcnt lgkmcnt(3)
	v_mfma_f32_16x16x32_bf16 v[130:133], v[114:117], v[34:37], 0
	v_add_u32_e32 v171, 16, v162
	v_add_u32_e32 v163, -16, v161
	v_cvt_f32_i32_e32 v169, v171
	s_waitcnt lgkmcnt(2)
	v_mfma_f32_16x16x32_bf16 v[130:133], v[118:121], v[30:33], v[130:133]
	v_cvt_f32_i32_e32 v165, v163
	v_cmp_gt_i32_e64 s[6:7], 0, v163
	v_mul_f32_e32 v169, v142, v169
	v_mfma_f32_16x16x32_bf16 v[114:117], v[114:117], v[26:29], 0
	v_mul_f32_e32 v165, v144, v165
	v_exp_f32_e32 v169, v169
	v_exp_f32_e32 v165, v165
	s_waitcnt lgkmcnt(1)
	v_mfma_f32_16x16x32_bf16 v[130:133], v[122:125], v[14:17], v[130:133]
	v_cmp_lt_i32_e32 vcc, 0, v163
	v_mul_f32_e32 v174, v154, v169
	v_mul_f32_e32 v173, v153, v165
	v_mfma_f32_16x16x32_bf16 v[114:117], v[118:121], v[22:25], v[114:117]
	v_cndmask_b32_e64 v170, 2.0, v174, s[6:7]
	v_cndmask_b32_e32 v170, v170, v173, vcc
	v_cmp_ne_u32_e64 s[6:7], s18, v162
	s_waitcnt lgkmcnt(0)
	v_mfma_f32_16x16x32_bf16 v[130:133], v[126:129], v[10:13], v[130:133]
	v_cmp_lt_i32_e32 vcc, 1, v163
	v_mul_f32_e32 v175, v151, v165
	v_mul_f32_e32 v177, v149, v165
	v_mfma_f32_16x16x32_bf16 v[114:117], v[122:125], v[6:9], v[114:117]
	v_mul_f32_e32 v179, v148, v165
	s_nop 2
	v_mul_f32_e32 v130, v170, v130
	v_mul_f32_e32 v170, v152, v169
	v_cndmask_b32_e64 v176, 2.0, v170, s[6:7]
	v_cndmask_b32_e32 v170, v176, v175, vcc
	v_mul_f32_e32 v131, v170, v131
	v_mul_f32_e32 v170, v150, v169
	v_cmp_ne_u32_e64 s[6:7], s21, v162
	v_mfma_f32_16x16x32_bf16 v[114:117], v[126:129], v[2:5], v[114:117]
	v_cmp_lt_i32_e32 vcc, 2, v163
	v_cndmask_b32_e64 v178, 2.0, v170, s[6:7]
	v_cmp_ne_u32_e64 s[6:7], s22, v162
	v_cndmask_b32_e32 v170, v178, v177, vcc
	v_cmp_lt_i32_e32 vcc, 3, v163
	v_mul_f32_e32 v163, v146, v169
	v_cndmask_b32_e64 v180, 2.0, v163, s[6:7]
	v_cndmask_b32_e32 v163, v180, v179, vcc
	v_mul_f32_e32 v114, v166, v114
	v_mul_f32_e32 v115, v167, v115
	v_mul_f32_e32 v132, v170, v132
	v_mul_f32_e32 v133, v163, v133
	v_cvt_pk_bf16_f32 v130, v130, v131
	v_cvt_pk_bf16_f32 v131, v132, v133
	ds_write_b64 v156, v[130:131] offset:53280
	v_mul_f32_e32 v116, v168, v116
	v_mul_f32_e32 v117, v164, v117
	v_cvt_pk_bf16_f32 v114, v114, v115
	v_cvt_pk_bf16_f32 v115, v116, v117
	ds_write_b64 v156, v[114:115] offset:55584
	ds_read_b128 v[114:117], v157 offset:8704
	ds_read_b128 v[118:121], v157 offset:8768
	ds_read_b128 v[122:125], v157 offset:8832
	ds_read_b128 v[126:129], v157 offset:8896
	s_waitcnt lgkmcnt(3)
	v_mfma_f32_16x16x32_bf16 v[130:133], v[114:117], v[34:37], 0
	v_add_u32_e32 v172, 32, v162
	v_subrev_u32_e32 v181, 32, v161
	v_cvt_f32_i32_e32 v164, v172
	s_waitcnt lgkmcnt(2)
	v_mfma_f32_16x16x32_bf16 v[130:133], v[118:121], v[30:33], v[130:133]
	v_cvt_f32_i32_e32 v163, v181
	v_cmp_gt_i32_e64 s[6:7], 0, v181
	v_mul_f32_e32 v164, v142, v164
	v_mfma_f32_16x16x32_bf16 v[114:117], v[114:117], v[26:29], 0
	v_mul_f32_e32 v163, v144, v163
	v_exp_f32_e32 v164, v164
	v_exp_f32_e32 v163, v163
	s_waitcnt lgkmcnt(1)
	v_mfma_f32_16x16x32_bf16 v[130:133], v[122:125], v[14:17], v[130:133]
	v_cmp_lt_i32_e32 vcc, 0, v181
	v_mul_f32_e32 v170, v154, v164
	v_mul_f32_e32 v169, v153, v163
	v_mfma_f32_16x16x32_bf16 v[114:117], v[118:121], v[22:25], v[114:117]
	v_cndmask_b32_e64 v165, 2.0, v170, s[6:7]
	v_cndmask_b32_e32 v165, v165, v169, vcc
	v_cmp_ne_u32_e64 s[6:7], s23, v162
	s_waitcnt lgkmcnt(0)
	v_mfma_f32_16x16x32_bf16 v[130:133], v[126:129], v[10:13], v[130:133]
	v_cmp_lt_i32_e32 vcc, 1, v181
	v_mul_f32_e32 v167, v151, v163
	v_mul_f32_e32 v166, v150, v164
	v_mfma_f32_16x16x32_bf16 v[114:117], v[122:125], v[6:9], v[114:117]
	s_add_i32 s19, s19, 64
	s_nop 2
	v_mul_f32_e32 v130, v165, v130
	v_mul_f32_e32 v165, v152, v164
	v_cndmask_b32_e64 v168, 2.0, v165, s[6:7]
	v_cndmask_b32_e32 v165, v168, v167, vcc
	v_cmp_ne_u32_e64 s[6:7], s24, v162
	v_mul_f32_e32 v131, v165, v131
	v_cmp_lt_i32_e32 vcc, 2, v181
	v_mul_f32_e32 v165, v149, v163
	v_cndmask_b32_e64 v166, 2.0, v166, s[6:7]
	v_mul_f32_e32 v164, v146, v164
	v_cmp_ne_u32_e64 s[6:7], s25, v162
	v_mfma_f32_16x16x32_bf16 v[114:117], v[126:129], v[2:5], v[114:117]
	v_cndmask_b32_e32 v182, v166, v165, vcc
	v_cmp_lt_i32_e32 vcc, 3, v181
	v_mul_f32_e32 v163, v148, v163
	v_cndmask_b32_e64 v164, 2.0, v164, s[6:7]
	v_cmp_ne_u32_e64 s[6:7], 0, v171
	v_mul_f32_e32 v132, v182, v132
	v_cndmask_b32_e32 v182, v164, v163, vcc
	v_cmp_lt_i32_e32 vcc, -16, v181
	v_cndmask_b32_e64 v118, 2.0, v174, s[6:7]
	v_mul_f32_e32 v133, v182, v133
	v_cndmask_b32_e32 v118, v118, v173, vcc
	v_cmp_lt_i32_e32 vcc, -15, v181
	v_mul_f32_e32 v114, v118, v114
	v_cvt_pk_bf16_f32 v130, v130, v131
	v_cvt_pk_bf16_f32 v131, v132, v133
	ds_write_b64 v156, v[130:131] offset:53312
	v_cndmask_b32_e32 v118, v176, v175, vcc
	v_cmp_lt_i32_e32 vcc, -14, v181
	v_mul_f32_e32 v115, v118, v115
	v_cvt_pk_bf16_f32 v114, v114, v115
	v_add_u32_e32 v174, 48, v162
	v_cndmask_b32_e32 v118, v178, v177, vcc
	v_cmp_lt_i32_e32 vcc, -13, v181
	v_mul_f32_e32 v116, v118, v116
	v_subrev_u32_e32 v171, 48, v161
	v_cndmask_b32_e32 v118, v180, v179, vcc
	v_mul_f32_e32 v117, v118, v117
	v_cvt_pk_bf16_f32 v115, v116, v117
	ds_write_b64 v156, v[114:115] offset:55616
	ds_read_b128 v[114:117], v157 offset:13056
	ds_read_b128 v[118:121], v157 offset:13120
	ds_read_b128 v[122:125], v157 offset:13184
	ds_read_b128 v[126:129], v157 offset:13248
	s_waitcnt lgkmcnt(3)
	v_mfma_f32_16x16x32_bf16 v[130:133], v[114:117], v[34:37], 0
	v_cvt_f32_i32_e32 v174, v174
	v_cvt_f32_i32_e32 v173, v171
	v_cmp_gt_i32_e64 s[6:7], 0, v171
	s_waitcnt lgkmcnt(2)
	v_mfma_f32_16x16x32_bf16 v[130:133], v[118:121], v[30:33], v[130:133]
	v_mul_f32_e32 v174, v142, v174
	v_mul_f32_e32 v173, v144, v173
	v_exp_f32_e32 v174, v174
	v_mfma_f32_16x16x32_bf16 v[114:117], v[114:117], v[26:29], 0
	v_exp_f32_e32 v173, v173
	v_cmp_lt_i32_e32 vcc, 0, v171
	v_mul_f32_e32 v176, v154, v174
	s_waitcnt lgkmcnt(1)
	v_mfma_f32_16x16x32_bf16 v[130:133], v[122:125], v[14:17], v[130:133]
	v_mul_f32_e32 v175, v153, v173
	v_cndmask_b32_e64 v176, 2.0, v176, s[6:7]
	v_cndmask_b32_e32 v175, v176, v175, vcc
	v_mfma_f32_16x16x32_bf16 v[114:117], v[118:121], v[22:25], v[114:117]
	v_mul_f32_e32 v176, v152, v174
	v_cmp_ne_u32_e64 s[6:7], s26, v162
	v_cmp_lt_i32_e32 vcc, 1, v171
	s_waitcnt lgkmcnt(0)
	v_mfma_f32_16x16x32_bf16 v[130:133], v[126:129], v[10:13], v[130:133]
	v_cndmask_b32_e64 v176, 2.0, v176, s[6:7]
	v_cmp_ne_u32_e64 s[6:7], s27, v162
	v_subrev_u32_e32 v161, 64, v161
	v_mfma_f32_16x16x32_bf16 v[114:117], v[122:125], v[6:9], v[114:117]
	s_cmpk_eq_i32 s19, 0xc0
	s_nop 2
	v_mul_f32_e32 v130, v175, v130
	v_mul_f32_e32 v175, v151, v173
	v_cndmask_b32_e32 v175, v176, v175, vcc
	v_mul_f32_e32 v176, v150, v174
	v_mul_f32_e32 v131, v175, v131
	v_cmp_lt_i32_e32 vcc, 2, v171
	v_mul_f32_e32 v175, v149, v173
	v_cndmask_b32_e64 v176, 2.0, v176, s[6:7]
	v_mul_f32_e32 v174, v146, v174
	v_cmp_ne_u32_e64 s[6:7], s28, v162
	v_mfma_f32_16x16x32_bf16 v[114:117], v[126:129], v[2:5], v[114:117]
	v_cndmask_b32_e32 v175, v176, v175, vcc
	v_cmp_lt_i32_e32 vcc, 3, v171
	v_mul_f32_e32 v173, v148, v173
	v_cndmask_b32_e64 v162, 2.0, v174, s[6:7]
	v_cmp_ne_u32_e64 s[6:7], 0, v172
	v_cndmask_b32_e32 v162, v162, v173, vcc
	v_cmp_lt_i32_e32 vcc, -16, v171
	v_cndmask_b32_e64 v118, 2.0, v170, s[6:7]
	v_mul_f32_e32 v132, v175, v132
	v_cndmask_b32_e32 v118, v118, v169, vcc
	v_cmp_lt_i32_e32 vcc, -15, v171
	v_mul_f32_e32 v114, v118, v114
	v_mul_f32_e32 v133, v162, v133
	v_cndmask_b32_e32 v118, v168, v167, vcc
	v_cmp_lt_i32_e32 vcc, -14, v171
	v_mul_f32_e32 v115, v118, v115
	v_cvt_pk_bf16_f32 v130, v130, v131
	v_cvt_pk_bf16_f32 v131, v132, v133
	ds_write_b64 v156, v[130:131] offset:53344
	v_cndmask_b32_e32 v118, v166, v165, vcc
	v_cmp_lt_i32_e32 vcc, -13, v171
	v_mul_f32_e32 v116, v118, v116
	v_cvt_pk_bf16_f32 v114, v114, v115
	s_nop 0
	v_cndmask_b32_e32 v118, v164, v163, vcc
	v_mul_f32_e32 v117, v118, v117
	v_cvt_pk_bf16_f32 v115, v116, v117
	ds_write_b64 v156, v[114:115] offset:55648
	s_waitcnt lgkmcnt(0)
	ds_read_b128 v[126:129], v147 offset:53248
	ds_read_b128 v[114:117], v147 offset:53312
	ds_read_b128 v[122:125], v147 offset:55552
	ds_read_b128 v[118:121], v147 offset:55616
	ds_read_b64_tr_b16 v[132:133], v137 offset:18496
	ds_read_b64_tr_b16 v[130:131], v137 offset:17408
	ds_read_b64_tr_b16 v[162:163], v137 offset:17440
	s_waitcnt lgkmcnt(1)
	v_mfma_f32_16x16x32_bf16 v[94:97], v[126:129], v[130:133], v[94:97]
	v_mfma_f32_16x16x32_bf16 v[82:85], v[122:125], v[130:133], v[82:85]
	ds_read_b64_tr_b16 v[130:131], v137 offset:26112
	ds_read_b64_tr_b16 v[132:133], v137 offset:27200
	ds_read_b64_tr_b16 v[164:165], v137 offset:18528
	s_waitcnt lgkmcnt(1)
	v_mfma_f32_16x16x32_bf16 v[94:97], v[114:117], v[130:133], v[94:97]
	v_mfma_f32_16x16x32_bf16 v[82:85], v[118:121], v[130:133], v[82:85]
	ds_read_b64_tr_b16 v[130:131], v137 offset:26144
	ds_read_b64_tr_b16 v[132:133], v137 offset:27232
	s_waitcnt lgkmcnt(2)
	v_mfma_f32_16x16x32_bf16 v[90:93], v[126:129], v[162:165], v[90:93]
	v_mfma_f32_16x16x32_bf16 v[70:73], v[122:125], v[162:165], v[70:73]
	s_waitcnt lgkmcnt(0)
	v_mfma_f32_16x16x32_bf16 v[90:93], v[114:117], v[130:133], v[90:93]
	v_mfma_f32_16x16x32_bf16 v[70:73], v[118:121], v[130:133], v[70:73]
	ds_read_b64_tr_b16 v[130:131], v137 offset:17472
	ds_read_b64_tr_b16 v[132:133], v137 offset:18560
	s_waitcnt lgkmcnt(0)
	v_mfma_f32_16x16x32_bf16 v[86:89], v[126:129], v[130:133], v[86:89]
	v_mfma_f32_16x16x32_bf16 v[66:69], v[122:125], v[130:133], v[66:69]
	ds_read_b64_tr_b16 v[130:131], v137 offset:26176
	ds_read_b64_tr_b16 v[132:133], v137 offset:27264
	s_waitcnt lgkmcnt(0)
	v_mfma_f32_16x16x32_bf16 v[86:89], v[114:117], v[130:133], v[86:89]
	v_mfma_f32_16x16x32_bf16 v[66:69], v[118:121], v[130:133], v[66:69]
	ds_read_b64_tr_b16 v[130:131], v137 offset:17504
	ds_read_b64_tr_b16 v[132:133], v137 offset:18592
	s_waitcnt lgkmcnt(0)
	v_mfma_f32_16x16x32_bf16 v[78:81], v[126:129], v[130:133], v[78:81]
	v_mfma_f32_16x16x32_bf16 v[62:65], v[122:125], v[130:133], v[62:65]
	ds_read_b64_tr_b16 v[130:131], v137 offset:26208
	ds_read_b64_tr_b16 v[132:133], v137 offset:27296
	s_waitcnt lgkmcnt(0)
	v_mfma_f32_16x16x32_bf16 v[78:81], v[114:117], v[130:133], v[78:81]
	v_mfma_f32_16x16x32_bf16 v[62:65], v[118:121], v[130:133], v[62:65]
	ds_read_b64_tr_b16 v[130:131], v137 offset:17536
	ds_read_b64_tr_b16 v[132:133], v137 offset:18624
	s_waitcnt lgkmcnt(0)
	v_mfma_f32_16x16x32_bf16 v[58:61], v[126:129], v[130:133], v[58:61]
	v_mfma_f32_16x16x32_bf16 v[46:49], v[122:125], v[130:133], v[46:49]
	ds_read_b64_tr_b16 v[130:131], v137 offset:26240
	ds_read_b64_tr_b16 v[132:133], v137 offset:27328
	s_waitcnt lgkmcnt(0)
	v_mfma_f32_16x16x32_bf16 v[58:61], v[114:117], v[130:133], v[58:61]
	v_mfma_f32_16x16x32_bf16 v[46:49], v[118:121], v[130:133], v[46:49]
	ds_read_b64_tr_b16 v[130:131], v137 offset:17568
	ds_read_b64_tr_b16 v[132:133], v137 offset:18656
	s_waitcnt lgkmcnt(0)
	v_mfma_f32_16x16x32_bf16 v[54:57], v[126:129], v[130:133], v[54:57]
	v_mfma_f32_16x16x32_bf16 v[42:45], v[122:125], v[130:133], v[42:45]
	ds_read_b64_tr_b16 v[130:131], v137 offset:26272
	ds_read_b64_tr_b16 v[132:133], v137 offset:27360
	s_waitcnt lgkmcnt(0)
	v_mfma_f32_16x16x32_bf16 v[54:57], v[114:117], v[130:133], v[54:57]
	v_mfma_f32_16x16x32_bf16 v[42:45], v[118:121], v[130:133], v[42:45]
	ds_read_b64_tr_b16 v[130:131], v137 offset:17600
	ds_read_b64_tr_b16 v[132:133], v137 offset:18688
	s_waitcnt lgkmcnt(0)
	v_mfma_f32_16x16x32_bf16 v[50:53], v[126:129], v[130:133], v[50:53]
	v_mfma_f32_16x16x32_bf16 v[38:41], v[122:125], v[130:133], v[38:41]
	ds_read_b64_tr_b16 v[130:131], v137 offset:26304
	ds_read_b64_tr_b16 v[132:133], v137 offset:27392
	s_waitcnt lgkmcnt(0)
	v_mfma_f32_16x16x32_bf16 v[50:53], v[114:117], v[130:133], v[50:53]
	v_mfma_f32_16x16x32_bf16 v[38:41], v[118:121], v[130:133], v[38:41]
	ds_read_b64_tr_b16 v[130:131], v137 offset:17632
	ds_read_b64_tr_b16 v[132:133], v137 offset:18720
	s_waitcnt lgkmcnt(0)
	v_mfma_f32_16x16x32_bf16 v[18:21], v[122:125], v[130:133], v[18:21]
	ds_read_b64_tr_b16 v[122:123], v137 offset:26336
	ds_read_b64_tr_b16 v[124:125], v137 offset:27424
	v_mfma_f32_16x16x32_bf16 v[74:77], v[126:129], v[130:133], v[74:77]
	s_waitcnt lgkmcnt(0)
	v_mfma_f32_16x16x32_bf16 v[74:77], v[114:117], v[122:125], v[74:77]
	v_mfma_f32_16x16x32_bf16 v[18:21], v[118:121], v[122:125], v[18:21]
	s_cbranch_scc0 .LBB0_372
	s_barrier
	s_waitcnt vmcnt(3)
	ds_write_b128 v136, v[98:101]
	s_waitcnt vmcnt(2)
	ds_write_b128 v136, v[102:105] offset:17408
	s_waitcnt vmcnt(1)
	ds_write_b128 v134, v[106:109]
	s_waitcnt vmcnt(0)
	ds_write_b128 v134, v[110:113] offset:17408
	s_waitcnt lgkmcnt(0)
	s_barrier
	ds_read_b128 v[98:101], v157
	ds_read_b128 v[102:105], v157 offset:64
	v_sub_u32_e32 v119, 0xc0, v155
	v_add_u32_e32 v118, 0xffffff40, v155
	v_cvt_f32_i32_e32 v119, v119
	v_cvt_f32_i32_e32 v118, v118
	s_waitcnt lgkmcnt(1)
	v_mfma_f32_16x16x32_bf16 v[106:109], v[98:101], v[34:37], 0
	ds_read_b128 v[110:113], v157 offset:128
	ds_read_b128 v[114:117], v157 offset:192
	v_mul_f32_e32 v119, v142, v119
	v_mul_f32_e32 v118, v144, v118
	v_mfma_f32_16x16x32_bf16 v[98:101], v[98:101], v[26:29], 0
	v_exp_f32_e32 v119, v119
	v_exp_f32_e32 v118, v118
	s_movk_i32 s0, 0xc0
	s_waitcnt lgkmcnt(2)
	v_mfma_f32_16x16x32_bf16 v[106:109], v[102:105], v[30:33], v[106:109]
	v_mul_f32_e32 v121, v119, v154
	v_cmp_ne_u32_e32 vcc, s0, v155
	v_mul_f32_e32 v120, v118, v153
	v_mfma_f32_16x16x32_bf16 v[98:101], v[102:105], v[22:25], v[98:101]
	v_sub_u32_e32 v103, 0xb0, v155
	v_add_u32_e32 v102, 0xffffff50, v155
	v_cvt_f32_i32_e32 v103, v103
	v_cvt_f32_i32_e32 v102, v102
	v_cndmask_b32_e32 v121, 2.0, v121, vcc
	v_cmp_lt_i32_e32 vcc, s0, v155
	s_movk_i32 s0, 0xc1
	v_mul_f32_e32 v122, v152, v119
	v_cndmask_b32_e32 v120, v121, v120, vcc
	v_cmp_ne_u32_e32 vcc, s0, v155
	v_mul_f32_e32 v121, v151, v118
	s_waitcnt lgkmcnt(1)
	v_mfma_f32_16x16x32_bf16 v[98:101], v[110:113], v[6:9], v[98:101]
	v_cndmask_b32_e32 v122, 2.0, v122, vcc
	v_cmp_lt_i32_e32 vcc, s0, v155
	s_movk_i32 s0, 0xc2
	v_mul_f32_e32 v103, v142, v103
	v_cndmask_b32_e32 v121, v122, v121, vcc
	v_mul_f32_e32 v123, v119, v150
	v_cmp_ne_u32_e32 vcc, s0, v155
	v_mul_f32_e32 v102, v144, v102
	v_exp_f32_e32 v103, v103
	v_mul_f32_e32 v122, v118, v149
	v_cndmask_b32_e32 v123, 2.0, v123, vcc
	v_cmp_lt_i32_e32 vcc, s0, v155
	s_movk_i32 s0, 0xc3
	v_exp_f32_e32 v102, v102
	v_cndmask_b32_e32 v122, v123, v122, vcc
	v_mul_f32_e32 v119, v119, v146
	v_cmp_ne_u32_e32 vcc, s0, v155
	v_mul_f32_e32 v118, v118, v148
	s_waitcnt lgkmcnt(0)
	v_mfma_f32_16x16x32_bf16 v[98:101], v[114:117], v[2:5], v[98:101]
	v_cndmask_b32_e32 v119, 2.0, v119, vcc
	v_cmp_lt_i32_e32 vcc, s0, v155
	s_movk_i32 s0, 0xb0
	v_mfma_f32_16x16x32_bf16 v[106:109], v[110:113], v[14:17], v[106:109]
	v_cndmask_b32_e32 v118, v119, v118, vcc
	v_mul_f32_e32 v105, v103, v154
	v_cmp_ne_u32_e32 vcc, s0, v155
	v_mul_f32_e32 v104, v102, v153
	v_mfma_f32_16x16x32_bf16 v[106:109], v[114:117], v[10:13], v[106:109]
	v_cndmask_b32_e32 v105, 2.0, v105, vcc
	v_cmp_lt_i32_e32 vcc, s0, v155
	s_movk_i32 s0, 0xb1
	v_sub_u32_e32 v123, 0xd0, v155
	v_cndmask_b32_e32 v104, v105, v104, vcc
	v_mul_f32_e32 v105, v152, v103
	v_cmp_ne_u32_e32 vcc, s0, v155
	v_mul_f32_e32 v98, v104, v98
	v_mul_f32_e32 v104, v151, v102
	v_cndmask_b32_e32 v105, 2.0, v105, vcc
	v_cmp_lt_i32_e32 vcc, s0, v155
	s_movk_i32 s0, 0xb2
	v_mul_f32_e32 v106, v120, v106
	v_cndmask_b32_e32 v104, v105, v104, vcc
	v_mul_f32_e32 v105, v103, v150
	v_cmp_ne_u32_e32 vcc, s0, v155
	v_mul_f32_e32 v99, v104, v99
	v_mul_f32_e32 v104, v102, v149
	v_cndmask_b32_e32 v105, 2.0, v105, vcc
	v_cmp_lt_i32_e32 vcc, s0, v155
	s_movk_i32 s0, 0xb3
	v_mul_f32_e32 v103, v103, v146
	v_cndmask_b32_e32 v104, v105, v104, vcc
	v_cmp_ne_u32_e32 vcc, s0, v155
	v_mul_f32_e32 v102, v102, v148
	v_mul_f32_e32 v107, v121, v107
	v_cndmask_b32_e32 v103, 2.0, v103, vcc
	v_cmp_lt_i32_e32 vcc, s0, v155
	v_mul_f32_e32 v108, v122, v108
	v_mul_f32_e32 v109, v118, v109
	v_cndmask_b32_e32 v102, v103, v102, vcc
	v_cvt_pk_bf16_f32 v106, v106, v107
	v_cvt_pk_bf16_f32 v107, v108, v109
	ds_write_b64 v156, v[106:107] offset:53248
	v_mul_f32_e32 v100, v104, v100
	v_mul_f32_e32 v101, v102, v101
	v_cvt_pk_bf16_f32 v98, v98, v99
	v_cvt_pk_bf16_f32 v99, v100, v101
	ds_write_b64 v156, v[98:99] offset:55552
	ds_read_b128 v[98:101], v157 offset:4352
	ds_read_b128 v[102:105], v157 offset:4416
	v_add_u32_e32 v119, 0xffffff30, v155
	v_cvt_f32_i32_e32 v123, v123
	v_cvt_f32_i32_e32 v119, v119
	s_waitcnt lgkmcnt(1)
	v_mfma_f32_16x16x32_bf16 v[106:109], v[98:101], v[34:37], 0
	ds_read_b128 v[110:113], v157 offset:4480
	ds_read_b128 v[114:117], v157 offset:4544
	v_mul_f32_e32 v123, v142, v123
	v_mul_f32_e32 v119, v144, v119
	v_mfma_f32_16x16x32_bf16 v[98:101], v[98:101], v[26:29], 0
	v_exp_f32_e32 v123, v123
	v_exp_f32_e32 v119, v119
	s_movk_i32 s0, 0xd0
	s_waitcnt lgkmcnt(2)
	v_mfma_f32_16x16x32_bf16 v[106:109], v[102:105], v[30:33], v[106:109]
	v_mul_f32_e32 v125, v123, v154
	v_cmp_ne_u32_e32 vcc, s0, v155
	v_mul_f32_e32 v124, v119, v153
	v_mfma_f32_16x16x32_bf16 v[98:101], v[102:105], v[22:25], v[98:101]
	v_cndmask_b32_e32 v125, 2.0, v125, vcc
	v_cmp_lt_i32_e32 vcc, s0, v155
	s_movk_i32 s0, 0xd1
	s_waitcnt lgkmcnt(1)
	v_mfma_f32_16x16x32_bf16 v[106:109], v[110:113], v[14:17], v[106:109]
	v_cndmask_b32_e32 v124, v125, v124, vcc
	v_mul_f32_e32 v126, v152, v123
	v_cmp_ne_u32_e32 vcc, s0, v155
	v_mfma_f32_16x16x32_bf16 v[98:101], v[110:113], v[6:9], v[98:101]
	v_mul_f32_e32 v125, v151, v119
	v_cndmask_b32_e32 v126, 2.0, v126, vcc
	v_cmp_lt_i32_e32 vcc, s0, v155
	s_movk_i32 s0, 0xd2
	v_mul_f32_e32 v127, v123, v150
	v_cndmask_b32_e32 v125, v126, v125, vcc
	v_cmp_ne_u32_e32 vcc, s0, v155
	s_waitcnt lgkmcnt(0)
	v_mfma_f32_16x16x32_bf16 v[106:109], v[114:117], v[10:13], v[106:109]
	v_mul_f32_e32 v126, v119, v149
	v_cndmask_b32_e32 v127, 2.0, v127, vcc
	v_cmp_lt_i32_e32 vcc, s0, v155
	s_movk_i32 s0, 0xd3
	v_mfma_f32_16x16x32_bf16 v[98:101], v[114:117], v[2:5], v[98:101]
	v_cndmask_b32_e32 v126, v127, v126, vcc
	v_mul_f32_e32 v123, v123, v146
	v_cmp_ne_u32_e32 vcc, s0, v155
	v_mul_f32_e32 v119, v119, v148
	v_mul_f32_e32 v106, v124, v106
	v_cndmask_b32_e32 v123, 2.0, v123, vcc
	v_cmp_lt_i32_e32 vcc, s0, v155
	s_nop 0
	v_mul_f32_e32 v98, v120, v98
	v_mul_f32_e32 v99, v121, v99
	v_cndmask_b32_e32 v119, v123, v119, vcc
	v_mul_f32_e32 v103, v119, v109
	v_mul_f32_e32 v107, v125, v107
	v_mul_f32_e32 v108, v126, v108
	v_cvt_pk_bf16_f32 v102, v106, v107
	v_cvt_pk_bf16_f32 v103, v108, v103
	ds_write_b64 v156, v[102:103] offset:53280
	v_mul_f32_e32 v100, v122, v100
	v_mul_f32_e32 v101, v118, v101
	v_cvt_pk_bf16_f32 v98, v98, v99
	v_cvt_pk_bf16_f32 v99, v100, v101
	ds_write_b64 v156, v[98:99] offset:55584
	ds_read_b128 v[98:101], v157 offset:8704
	ds_read_b128 v[102:105], v157 offset:8768
	v_sub_u32_e32 v120, 0xe0, v155
	v_add_u32_e32 v118, 0xffffff20, v155
	v_cvt_f32_i32_e32 v120, v120
	v_cvt_f32_i32_e32 v118, v118
	s_waitcnt lgkmcnt(1)
	v_mfma_f32_16x16x32_bf16 v[106:109], v[98:101], v[34:37], 0
	ds_read_b128 v[110:113], v157 offset:8832
	ds_read_b128 v[114:117], v157 offset:8896
	v_mul_f32_e32 v120, v142, v120
	v_mul_f32_e32 v118, v144, v118
	v_mfma_f32_16x16x32_bf16 v[98:101], v[98:101], v[26:29], 0
	v_exp_f32_e32 v120, v120
	v_exp_f32_e32 v118, v118
	s_movk_i32 s0, 0xe0
	s_waitcnt lgkmcnt(2)
	v_mfma_f32_16x16x32_bf16 v[106:109], v[102:105], v[30:33], v[106:109]
	v_mul_f32_e32 v122, v120, v154
	v_cmp_ne_u32_e32 vcc, s0, v155
	v_mul_f32_e32 v121, v118, v153
	v_mfma_f32_16x16x32_bf16 v[98:101], v[102:105], v[22:25], v[98:101]
	v_cndmask_b32_e32 v122, 2.0, v122, vcc
	v_cmp_lt_i32_e32 vcc, s0, v155
	s_movk_i32 s0, 0xe1
	s_waitcnt lgkmcnt(1)
	v_mfma_f32_16x16x32_bf16 v[106:109], v[110:113], v[14:17], v[106:109]
	v_cndmask_b32_e32 v121, v122, v121, vcc
	v_mul_f32_e32 v123, v152, v120
	v_cmp_ne_u32_e32 vcc, s0, v155
	v_mfma_f32_16x16x32_bf16 v[98:101], v[110:113], v[6:9], v[98:101]
	v_mul_f32_e32 v122, v151, v118
	v_cndmask_b32_e32 v123, 2.0, v123, vcc
	v_cmp_lt_i32_e32 vcc, s0, v155
	s_movk_i32 s0, 0xe2
	v_mul_f32_e32 v127, v120, v150
	v_cndmask_b32_e32 v122, v123, v122, vcc
	v_cmp_ne_u32_e32 vcc, s0, v155
	s_waitcnt lgkmcnt(0)
	v_mfma_f32_16x16x32_bf16 v[106:109], v[114:117], v[10:13], v[106:109]
	v_mul_f32_e32 v123, v118, v149
	v_cndmask_b32_e32 v127, 2.0, v127, vcc
	v_cmp_lt_i32_e32 vcc, s0, v155
	s_movk_i32 s0, 0xe3
	v_mfma_f32_16x16x32_bf16 v[98:101], v[114:117], v[2:5], v[98:101]
	v_cndmask_b32_e32 v123, v127, v123, vcc
	v_mul_f32_e32 v120, v120, v146
	v_cmp_ne_u32_e32 vcc, s0, v155
	v_mul_f32_e32 v118, v118, v148
	v_mul_f32_e32 v106, v121, v106
	v_cndmask_b32_e32 v120, 2.0, v120, vcc
	v_cmp_lt_i32_e32 vcc, s0, v155
	s_nop 0
	v_mul_f32_e32 v98, v124, v98
	v_mul_f32_e32 v99, v125, v99
	v_cndmask_b32_e32 v118, v120, v118, vcc
	v_mul_f32_e32 v103, v118, v109
	v_mul_f32_e32 v107, v122, v107
	v_mul_f32_e32 v108, v123, v108
	v_cvt_pk_bf16_f32 v102, v106, v107
	v_cvt_pk_bf16_f32 v103, v108, v103
	ds_write_b64 v156, v[102:103] offset:53312
	v_mul_f32_e32 v100, v126, v100
	v_mul_f32_e32 v101, v119, v101
	v_cvt_pk_bf16_f32 v98, v98, v99
	v_cvt_pk_bf16_f32 v99, v100, v101
	ds_write_b64 v156, v[98:99] offset:55616
	ds_read_b128 v[98:101], v157 offset:13056
	ds_read_b128 v[102:105], v157 offset:13120
	s_waitcnt lgkmcnt(1)
	v_mfma_f32_16x16x32_bf16 v[106:109], v[98:101], v[34:37], 0
	v_sub_u32_e32 v120, 0xf0, v155
	ds_read_b128 v[110:113], v157 offset:13184
	ds_read_b128 v[114:117], v157 offset:13248
	v_add_u32_e32 v119, 0xffffff10, v155
	s_waitcnt lgkmcnt(2)
	v_mfma_f32_16x16x32_bf16 v[106:109], v[102:105], v[30:33], v[106:109]
	v_cvt_f32_i32_e32 v120, v120
	v_cvt_f32_i32_e32 v119, v119
	s_movk_i32 s0, 0xf0
	v_mfma_f32_16x16x32_bf16 v[98:101], v[98:101], v[26:29], 0
	v_mul_f32_e32 v120, v142, v120
	v_mul_f32_e32 v119, v144, v119
	v_exp_f32_e32 v120, v120
	s_waitcnt lgkmcnt(1)
	v_mfma_f32_16x16x32_bf16 v[106:109], v[110:113], v[14:17], v[106:109]
	v_exp_f32_e32 v119, v119
	v_cmp_ne_u32_e32 vcc, s0, v155
	v_mul_f32_e32 v125, v120, v154
	v_mfma_f32_16x16x32_bf16 v[98:101], v[102:105], v[22:25], v[98:101]
	v_mul_f32_e32 v124, v119, v153
	v_cndmask_b32_e32 v125, 2.0, v125, vcc
	v_cmp_lt_i32_e32 vcc, s0, v155
	s_waitcnt lgkmcnt(0)
	v_mfma_f32_16x16x32_bf16 v[106:109], v[114:117], v[10:13], v[106:109]
	s_movk_i32 s0, 0xf1
	v_cndmask_b32_e32 v124, v125, v124, vcc
	v_mul_f32_e32 v125, v152, v120
	v_mfma_f32_16x16x32_bf16 v[98:101], v[110:113], v[6:9], v[98:101]
	v_cmp_ne_u32_e32 vcc, s0, v155
	s_nop 2
	v_mul_f32_e32 v106, v124, v106
	v_mul_f32_e32 v124, v151, v119
	v_cndmask_b32_e32 v125, 2.0, v125, vcc
	v_cmp_lt_i32_e32 vcc, s0, v155
	s_movk_i32 s0, 0xf2
	v_mfma_f32_16x16x32_bf16 v[98:101], v[114:117], v[2:5], v[98:101]
	v_cndmask_b32_e32 v124, v125, v124, vcc
	v_mul_f32_e32 v125, v120, v150
	v_cmp_ne_u32_e32 vcc, s0, v155
	v_mul_f32_e32 v107, v124, v107
	v_mul_f32_e32 v124, v119, v149
	v_cndmask_b32_e32 v125, 2.0, v125, vcc
	v_cmp_lt_i32_e32 vcc, s0, v155
	s_movk_i32 s0, 0xf3
	v_mul_f32_e32 v120, v120, v146
	v_cndmask_b32_e32 v124, v125, v124, vcc
	v_cmp_ne_u32_e32 vcc, s0, v155
	v_mul_f32_e32 v119, v119, v148
	v_mul_f32_e32 v98, v121, v98
	v_cndmask_b32_e32 v120, 2.0, v120, vcc
	v_cmp_lt_i32_e32 vcc, s0, v155
	v_mul_f32_e32 v99, v122, v99
	v_mul_f32_e32 v108, v124, v108
	v_cndmask_b32_e32 v102, v120, v119, vcc
	v_mul_f32_e32 v103, v102, v109
	v_cvt_pk_bf16_f32 v102, v106, v107
	v_cvt_pk_bf16_f32 v103, v108, v103
	ds_write_b64 v156, v[102:103] offset:53344
	v_mul_f32_e32 v100, v123, v100
	v_mul_f32_e32 v101, v118, v101
	v_cvt_pk_bf16_f32 v98, v98, v99
	v_cvt_pk_bf16_f32 v99, v100, v101
	ds_write_b64 v156, v[98:99] offset:55648
	s_waitcnt lgkmcnt(0)
	ds_read_b128 v[102:105], v147 offset:53248
	ds_read_b128 v[106:109], v147 offset:53312
	ds_read_b64_tr_b16 v[100:101], v137 offset:18496
	ds_read_b64_tr_b16 v[98:99], v137 offset:17408
	ds_read_b64_tr_b16 v[110:111], v137 offset:17440
	ds_read_b64_tr_b16 v[114:115], v137 offset:17472
	ds_read_b64_tr_b16 v[118:119], v137 offset:17504
	ds_read_b64_tr_b16 v[112:113], v137 offset:18528
	ds_read_b64_tr_b16 v[116:117], v137 offset:18560
	ds_read_b64_tr_b16 v[120:121], v137 offset:18592
	s_waitcnt lgkmcnt(6)
	v_mfma_f32_16x16x32_bf16 v[94:97], v[102:105], v[98:101], v[94:97]
	ds_read_b128 v[122:125], v147 offset:55552
	ds_read_b128 v[126:129], v147 offset:55616
	ds_read_b64_tr_b16 v[132:133], v137 offset:27200
	ds_read_b64_tr_b16 v[130:131], v137 offset:26112
	ds_read_b64_tr_b16 v[146:147], v137 offset:26144
	ds_read_b64_tr_b16 v[150:151], v137 offset:26176
	ds_read_b64_tr_b16 v[154:155], v137 offset:26208
	ds_read_b64_tr_b16 v[148:149], v137 offset:27232
	ds_read_b64_tr_b16 v[152:153], v137 offset:27264
	ds_read_b64_tr_b16 v[156:157], v137 offset:27296
	s_mov_b32 s7, 0
	s_waitcnt lgkmcnt(12)
	v_mfma_f32_16x16x32_bf16 v[90:93], v[102:105], v[110:113], v[90:93]
	s_andn2_b64 vcc, exec, s[30:31]
	s_waitcnt lgkmcnt(9)
	v_mfma_f32_16x16x32_bf16 v[82:85], v[122:125], v[98:101], v[82:85]
	s_waitcnt lgkmcnt(6)
	v_mfma_f32_16x16x32_bf16 v[98:101], v[106:109], v[130:133], v[94:97]
	v_mfma_f32_16x16x32_bf16 v[70:73], v[122:125], v[110:113], v[70:73]
	s_waitcnt lgkmcnt(2)
	v_mfma_f32_16x16x32_bf16 v[94:97], v[106:109], v[146:149], v[90:93]
	v_mfma_f32_16x16x32_bf16 v[86:89], v[102:105], v[114:117], v[86:89]
	v_mfma_f32_16x16x32_bf16 v[66:69], v[122:125], v[114:117], v[66:69]
	v_mfma_f32_16x16x32_bf16 v[78:81], v[102:105], v[118:121], v[78:81]
	v_mfma_f32_16x16x32_bf16 v[62:65], v[122:125], v[118:121], v[62:65]
	ds_read_b64_tr_b16 v[92:93], v137 offset:18624
	ds_read_b64_tr_b16 v[90:91], v137 offset:17536
	ds_read_b64_tr_b16 v[110:111], v137 offset:17568
	ds_read_b64_tr_b16 v[114:115], v137 offset:17600
	ds_read_b64_tr_b16 v[118:119], v137 offset:17632
	ds_read_b64_tr_b16 v[112:113], v137 offset:18656
	ds_read_b64_tr_b16 v[116:117], v137 offset:18688
	ds_read_b64_tr_b16 v[120:121], v137 offset:18720
	s_waitcnt lgkmcnt(6)
	v_mfma_f32_16x16x32_bf16 v[58:61], v[102:105], v[90:93], v[58:61]
	s_waitcnt lgkmcnt(2)
	v_mfma_f32_16x16x32_bf16 v[54:57], v[102:105], v[110:113], v[54:57]
	v_mfma_f32_16x16x32_bf16 v[82:85], v[126:129], v[130:133], v[82:85]
	v_mfma_f32_16x16x32_bf16 v[70:73], v[126:129], v[146:149], v[70:73]
	v_mfma_f32_16x16x32_bf16 v[86:89], v[106:109], v[150:153], v[86:89]
	v_mfma_f32_16x16x32_bf16 v[66:69], v[126:129], v[150:153], v[66:69]
	v_mfma_f32_16x16x32_bf16 v[78:81], v[106:109], v[154:157], v[78:81]
	v_mfma_f32_16x16x32_bf16 v[62:65], v[126:129], v[154:157], v[62:65]
	ds_read_b64_tr_b16 v[132:133], v137 offset:27328
	ds_read_b64_tr_b16 v[130:131], v137 offset:26240
	ds_read_b64_tr_b16 v[146:147], v137 offset:26272
	ds_read_b64_tr_b16 v[150:151], v137 offset:26304
	ds_read_b64_tr_b16 v[154:155], v137 offset:26336
	ds_read_b64_tr_b16 v[148:149], v137 offset:27360
	ds_read_b64_tr_b16 v[152:153], v137 offset:27392
	ds_read_b64_tr_b16 v[156:157], v137 offset:27424
	v_mfma_f32_16x16x32_bf16 v[46:49], v[122:125], v[90:93], v[46:49]
	s_waitcnt lgkmcnt(6)
	v_mfma_f32_16x16x32_bf16 v[90:93], v[106:109], v[130:133], v[58:61]
	v_mfma_f32_16x16x32_bf16 v[42:45], v[122:125], v[110:113], v[42:45]
	s_waitcnt lgkmcnt(2)
	v_mfma_f32_16x16x32_bf16 v[58:61], v[106:109], v[146:149], v[54:57]
	v_mfma_f32_16x16x32_bf16 v[50:53], v[102:105], v[114:117], v[50:53]
	v_mfma_f32_16x16x32_bf16 v[38:41], v[122:125], v[114:117], v[38:41]
	v_mfma_f32_16x16x32_bf16 v[54:57], v[102:105], v[118:121], v[74:77]
	v_mfma_f32_16x16x32_bf16 v[18:21], v[122:125], v[118:121], v[18:21]
	v_mfma_f32_16x16x32_bf16 v[46:49], v[126:129], v[130:133], v[46:49]
	v_mfma_f32_16x16x32_bf16 v[42:45], v[126:129], v[146:149], v[42:45]
	s_waitcnt lgkmcnt(1)
	v_mfma_f32_16x16x32_bf16 v[50:53], v[106:109], v[150:153], v[50:53]
	v_mfma_f32_16x16x32_bf16 v[38:41], v[126:129], v[150:153], v[38:41]
	s_waitcnt lgkmcnt(0)
	v_mfma_f32_16x16x32_bf16 v[54:57], v[106:109], v[154:157], v[54:57]
	v_mfma_f32_16x16x32_bf16 v[18:21], v[126:129], v[154:157], v[18:21]
	s_cbranch_vccnz .LBB0_375
	v_ashrrev_i32_e32 v110, 2, v140
	s_add_u32 s0, s94, s16
	v_lshlrev_b32_e32 v74, 7, v110
	s_addc_u32 s1, s95, s17
	v_ashrrev_i32_e32 v75, 31, v74
	v_lshlrev_b32_e32 v76, 5, v140
	v_lshl_add_u64 v[74:75], v[74:75], 1, s[0:1]
	v_and_b32_e32 v76, 0x60, v76
	v_mov_b32_e32 v77, 0
	v_lshl_add_u64 v[74:75], v[74:75], 0, v[76:77]
	v_readlane_b32 s98, v242, 40
	v_readlane_b32 s99, v242, 41
	s_nop 3
	s_and_saveexec_b64 s[100:101], s[98:99]
	s_cbranch_execz .Lp5a_done
	s_getreg_b32 s98, hwreg(HW_REG_XCC_ID, 0, 4)
	s_lshl_b32 s98, s98, 8
	v_mov_b32_e32 v102, s98
	v_add_u32_e32 v102, 0x6400, v102
	v_mov_b32_e32 v103, 3
	s_mov_b32 s99, 0
.Lp5a_spin:
	global_load_dword v104, v102, s[54:55] sc1
	s_waitcnt vmcnt(0)
	v_cmp_ge_u32_e32 vcc, v104, v103
	s_cbranch_vccnz .Lp5a_done
	s_add_i32 s99, s99, 1
	s_cmp_gt_u32 s99, 0x40000
	s_cbranch_scc1 .Lp5a_done
	s_sleep 1
	s_branch .Lp5a_spin
.Lp5a_done:
	s_or_b64 exec, exec, s[100:101]
	s_barrier
	global_load_dwordx4 v[102:105], v[74:75], off
	global_load_dwordx4 v[106:109], v[74:75], off offset:16
	s_mov_b64 s[98:99], 0x8000
	v_lshl_add_u64 v[216:217], v[74:75], 0, s[98:99]
	global_load_dwordx4 v[220:223], v[74:75], off offset:128
	global_load_dwordx4 v[224:227], v[74:75], off offset:144
	global_load_dwordx4 v[228:231], v[216:217], off
	global_load_dwordx4 v[232:235], v[216:217], off offset:16
	global_load_dwordx4 v[236:239], v[216:217], off offset:128
	global_load_dwordx4 v[208:211], v[216:217], off offset:144
	v_add_u32_e32 v77, 1, v143
	v_add_u32_e32 v111, 17, v143
	v_lshlrev_b32_e32 v134, 16, v26
	v_and_b32_e32 v136, 0xffff0000, v26
	v_cvt_f32_i32_e32 v26, v77
	v_lshlrev_b32_e32 v126, 16, v30
	v_and_b32_e32 v127, 0xffff0000, v30
	v_cvt_f32_i32_e32 v30, v111
	s_movk_i32 s0, 0x90
	v_lshlrev_b32_e32 v138, 16, v28
	v_and_b32_e32 v139, 0xffff0000, v28
	v_mul_lo_u32 v28, v110, s0
	v_mul_f32_e32 v26, v144, v26
	v_exp_f32_e32 v140, v26
	v_add3_u32 v26, 0, v28, v76
	v_mul_f32_e32 v28, v144, v30
	v_exp_f32_e32 v144, v28
	v_lshlrev_b32_e32 v120, 16, v35
	v_and_b32_e32 v121, 0xffff0000, v35
	v_lshlrev_b32_e32 v122, 16, v36
	v_and_b32_e32 v125, 0xffff0000, v37
	v_lshlrev_b32_e32 v130, 16, v32
	v_lshlrev_b32_e32 v137, 16, v27
	v_and_b32_e32 v27, 0xffff0000, v27
	v_lshlrev_b32_e32 v118, 16, v34
	v_and_b32_e32 v119, 0xffff0000, v34
	v_and_b32_e32 v123, 0xffff0000, v36
	v_lshlrev_b32_e32 v124, 16, v37
	v_lshlrev_b32_e32 v128, 16, v31
	v_and_b32_e32 v129, 0xffff0000, v31
	v_and_b32_e32 v131, 0xffff0000, v32
	v_lshlrev_b32_e32 v132, 16, v33
	v_and_b32_e32 v133, 0xffff0000, v33
	v_mul_f32_e32 v31, v140, v120
	v_mul_f32_e32 v32, v140, v121
	v_mul_f32_e32 v33, v140, v122
	v_mul_f32_e32 v36, v140, v125
	v_mul_f32_e32 v111, v140, v130
	v_mul_f32_e32 v146, v144, v27
	v_mul_f32_e32 v28, v140, v118
	v_mul_f32_e32 v30, v140, v119
	v_mul_f32_e32 v34, v140, v123
	v_mul_f32_e32 v35, v140, v124
	v_mul_f32_e32 v112, v140, v131
	v_mul_f32_e32 v117, v144, v137
	v_mul_f32_e32 v147, v144, v138
	v_mul_f32_e32 v148, v144, v139
	v_cvt_pk_bf16_f32 v31, v31, v32
	v_cvt_pk_bf16_f32 v32, v33, v34
	v_cvt_pk_bf16_f32 v33, v35, v36
	v_cvt_pk_bf16_f32 v36, v111, v112
	v_cvt_pk_bf16_f32 v111, v117, v146
	v_lshlrev_b32_e32 v146, 16, v29
	v_and_b32_e32 v149, 0xffff0000, v22
	v_mul_f32_e32 v37, v140, v126
	v_mul_f32_e32 v113, v140, v132
	v_cvt_pk_bf16_f32 v30, v28, v30
	v_cvt_pk_bf16_f32 v112, v147, v148
	v_mul_f32_e32 v28, v144, v146
	v_and_b32_e32 v147, 0xffff0000, v29
	v_lshlrev_b32_e32 v148, 16, v22
	v_mul_f32_e32 v22, v144, v149
	v_mul_f32_e32 v76, v140, v127
	v_mul_f32_e32 v114, v140, v133
	v_cvt_pk_bf16_f32 v34, v37, v76
	v_cvt_pk_bf16_f32 v37, v113, v114
	v_mul_f32_e32 v29, v144, v147
	v_cvt_pk_bf16_f32 v113, v28, v29
	v_mul_f32_e32 v28, v144, v148
	v_mul_f32_e32 v110, v140, v129
	v_mul_f32_e32 v115, v144, v134
	s_waitcnt vmcnt(7)
	ds_write_b128 v26, v[102:105] offset:34816
	s_waitcnt vmcnt(6)
	ds_write_b128 v26, v[106:109] offset:34832
	v_cvt_pk_bf16_f32 v102, v28, v22
	v_add_u32_e32 v22, v145, v135
	s_waitcnt lgkmcnt(0)
	s_barrier
	ds_read_b128 v[104:107], v22 offset:34816
	v_mul_f32_e32 v116, v144, v136
	v_mul_f32_e32 v77, v140, v128
	v_cvt_pk_bf16_f32 v35, v77, v110
	v_cvt_pk_bf16_f32 v110, v115, v116
	ds_read_b128 v[114:117], v22 offset:34880
	s_waitcnt lgkmcnt(1)
	v_mfma_f32_16x16x32_bf16 v[98:101], v[30:33], v[104:107], v[98:101]
	v_and_b32_e32 v151, 0xffff0000, v23
	v_lshlrev_b32_e32 v150, 16, v23
	v_mul_f32_e32 v23, v144, v151
	v_mfma_f32_16x16x32_bf16 v[82:85], v[110:113], v[104:107], v[82:85]
	v_lshlrev_b32_e32 v135, 16, v24
	v_and_b32_e32 v152, 0xffff0000, v24
	v_mul_f32_e32 v28, v144, v150
	v_cvt_pk_bf16_f32 v103, v28, v23
	v_mul_f32_e32 v23, v144, v135
	v_mul_f32_e32 v24, v144, v152
	v_lshlrev_b32_e32 v153, 16, v25
	v_and_b32_e32 v154, 0xffff0000, v25
	v_cvt_pk_bf16_f32 v104, v23, v24
	v_mul_f32_e32 v23, v144, v153
	s_waitcnt lgkmcnt(0)
	v_mfma_f32_16x16x32_bf16 v[98:101], v[34:37], v[114:117], v[98:101]
	v_mul_f32_e32 v24, v144, v154
	v_cvt_pk_bf16_f32 v105, v23, v24
	v_or_b32_e32 v23, 32, v141
	v_mfma_f32_16x16x32_bf16 v[82:85], v[102:105], v[114:117], v[82:85]
	ds_read_b128 v[106:109], v22 offset:37120
	ds_read_b128 v[114:117], v22 offset:37184
	v_mad_u32_u24 v23, v23, s0, v145
	v_lshlrev_b32_e32 v141, 16, v10
	s_waitcnt lgkmcnt(1)
	v_mfma_f32_16x16x32_bf16 v[94:97], v[30:33], v[106:109], v[94:97]
	v_and_b32_e32 v145, 0xffff0000, v10
	v_mul_f32_e32 v10, v140, v145
	v_lshlrev_b32_e32 v155, 16, v11
	v_mfma_f32_16x16x32_bf16 v[70:73], v[110:113], v[106:109], v[70:73]
	v_and_b32_e32 v156, 0xffff0000, v11
	v_mul_f32_e32 v11, v140, v156
	v_lshlrev_b32_e32 v157, 16, v12
	s_waitcnt lgkmcnt(0)
	v_mfma_f32_16x16x32_bf16 v[94:97], v[34:37], v[114:117], v[94:97]
	v_and_b32_e32 v158, 0xffff0000, v12
	v_mul_f32_e32 v12, v140, v158
	v_lshlrev_b32_e32 v159, 16, v13
	v_mfma_f32_16x16x32_bf16 v[70:73], v[102:105], v[114:117], v[70:73]
	ds_read_b128 v[106:109], v23 offset:34816
	ds_read_b128 v[114:117], v23 offset:34880
	v_and_b32_e32 v160, 0xffff0000, v13
	v_mul_f32_e32 v13, v140, v160
	s_waitcnt lgkmcnt(1)
	v_mfma_f32_16x16x32_bf16 v[86:89], v[30:33], v[106:109], v[86:89]
	v_and_b32_e32 v161, 0xffff0000, v6
	v_lshlrev_b32_e32 v162, 16, v7
	v_and_b32_e32 v163, 0xffff0000, v7
	v_mfma_f32_16x16x32_bf16 v[66:69], v[110:113], v[106:109], v[66:69]
	v_mul_f32_e32 v7, v144, v163
	v_lshlrev_b32_e32 v164, 16, v8
	v_and_b32_e32 v165, 0xffff0000, v8
	s_waitcnt lgkmcnt(0)
	v_mfma_f32_16x16x32_bf16 v[86:89], v[34:37], v[114:117], v[86:89]
	v_and_b32_e32 v167, 0xffff0000, v9
	v_mul_f32_e32 v8, v144, v165
	v_lshlrev_b32_e32 v166, 16, v9
	v_mfma_f32_16x16x32_bf16 v[66:69], v[102:105], v[114:117], v[66:69]
	ds_read_b128 v[106:109], v23 offset:37120
	ds_read_b128 v[114:117], v23 offset:37184
	v_mul_f32_e32 v9, v144, v167
	v_lshlrev_b32_e32 v168, 16, v2
	s_waitcnt lgkmcnt(1)
	v_mfma_f32_16x16x32_bf16 v[76:79], v[30:33], v[106:109], v[78:81]
	v_and_b32_e32 v169, 0xffff0000, v2
	v_mul_f32_e32 v2, v144, v169
	v_lshlrev_b32_e32 v170, 16, v3
	v_mfma_f32_16x16x32_bf16 v[62:65], v[110:113], v[106:109], v[62:65]
	v_and_b32_e32 v171, 0xffff0000, v3
	v_mul_f32_e32 v3, v144, v171
	v_lshlrev_b32_e32 v172, 16, v4
	s_waitcnt lgkmcnt(0)
	v_mfma_f32_16x16x32_bf16 v[76:79], v[34:37], v[114:117], v[76:79]
	v_and_b32_e32 v173, 0xffff0000, v4
	v_and_b32_e32 v175, 0xffff0000, v5
	v_mul_f32_e32 v4, v144, v173
	v_mfma_f32_16x16x32_bf16 v[62:65], v[102:105], v[114:117], v[62:65]
	ds_read_b128 v[106:109], v22 offset:44032
	ds_read_b128 v[114:117], v22 offset:44096
	v_lshlrev_b32_e32 v174, 16, v5
	v_mul_f32_e32 v5, v144, v175
	s_waitcnt lgkmcnt(1)
	v_mfma_f32_16x16x32_bf16 v[90:93], v[30:33], v[106:109], v[90:93]
	s_mov_b64 s[0:1], 0x8000
	v_mfma_f32_16x16x32_bf16 v[46:49], v[110:113], v[106:109], v[46:49]
	s_waitcnt lgkmcnt(0)
	v_mfma_f32_16x16x32_bf16 v[90:93], v[34:37], v[114:117], v[90:93]
	v_mfma_f32_16x16x32_bf16 v[46:49], v[102:105], v[114:117], v[46:49]
	ds_read_b128 v[106:109], v22 offset:46336
	ds_read_b128 v[114:117], v22 offset:46400
	s_waitcnt lgkmcnt(1)
	v_mfma_f32_16x16x32_bf16 v[58:61], v[30:33], v[106:109], v[58:61]
	v_mfma_f32_16x16x32_bf16 v[42:45], v[110:113], v[106:109], v[42:45]
	s_waitcnt lgkmcnt(0)
	v_mfma_f32_16x16x32_bf16 v[58:61], v[34:37], v[114:117], v[58:61]
	v_mfma_f32_16x16x32_bf16 v[42:45], v[102:105], v[114:117], v[42:45]
	ds_read_b128 v[106:109], v22 offset:48640
	ds_read_b128 v[114:117], v22 offset:48704
	s_waitcnt lgkmcnt(1)
	v_mfma_f32_16x16x32_bf16 v[50:53], v[30:33], v[106:109], v[50:53]
	v_mfma_f32_16x16x32_bf16 v[38:41], v[110:113], v[106:109], v[38:41]
	s_waitcnt lgkmcnt(0)
	v_mfma_f32_16x16x32_bf16 v[50:53], v[34:37], v[114:117], v[50:53]
	v_mfma_f32_16x16x32_bf16 v[38:41], v[102:105], v[114:117], v[38:41]
	ds_read_b128 v[106:109], v22 offset:50944
	ds_read_b128 v[114:117], v22 offset:51008
	s_waitcnt lgkmcnt(0)
	s_barrier
	v_mfma_f32_16x16x32_bf16 v[28:31], v[30:33], v[106:109], v[54:57]
	v_mfma_f32_16x16x32_bf16 v[28:31], v[34:37], v[114:117], v[28:31]
	s_nop 0
	s_waitcnt vmcnt(5)
	ds_write_b128 v26, v[220:223] offset:34816
	s_waitcnt vmcnt(4)
	ds_write_b128 v26, v[224:227] offset:34832
	v_mfma_f32_16x16x32_bf16 v[18:21], v[110:113], v[106:109], v[18:21]
	v_lshlrev_b32_e32 v110, 16, v14
	v_and_b32_e32 v111, 0xffff0000, v14
	v_mul_f32_e32 v24, v140, v110
	v_mul_f32_e32 v14, v140, v111
	v_lshlrev_b32_e32 v112, 16, v15
	v_and_b32_e32 v113, 0xffff0000, v15
	v_mfma_f32_16x16x32_bf16 v[18:21], v[102:105], v[114:117], v[18:21]
	v_cvt_pk_bf16_f32 v14, v24, v14
	v_mul_f32_e32 v24, v140, v112
	v_mul_f32_e32 v15, v140, v113
	v_lshlrev_b32_e32 v114, 16, v16
	v_and_b32_e32 v115, 0xffff0000, v16
	v_cvt_pk_bf16_f32 v15, v24, v15
	v_mul_f32_e32 v24, v140, v114
	v_mul_f32_e32 v16, v140, v115
	v_lshlrev_b32_e32 v116, 16, v17
	v_and_b32_e32 v117, 0xffff0000, v17
	v_cvt_pk_bf16_f32 v16, v24, v16
	v_mul_f32_e32 v24, v140, v116
	v_mul_f32_e32 v17, v140, v117
	v_cvt_pk_bf16_f32 v17, v24, v17
	v_mul_f32_e32 v24, v140, v141
	v_cvt_pk_bf16_f32 v10, v24, v10
	v_mul_f32_e32 v24, v140, v155
	s_waitcnt lgkmcnt(0)
	s_barrier
	v_cvt_pk_bf16_f32 v11, v24, v11
	v_mul_f32_e32 v24, v140, v157
	ds_read_b128 v[32:35], v22 offset:34816
	ds_read_b128 v[54:57], v22 offset:34880
	v_cvt_pk_bf16_f32 v12, v24, v12
	v_mul_f32_e32 v24, v140, v159
	v_lshlrev_b32_e32 v140, 16, v6
	v_cvt_pk_bf16_f32 v13, v24, v13
	v_mul_f32_e32 v24, v144, v140
	v_mul_f32_e32 v6, v144, v161
	v_cvt_pk_bf16_f32 v6, v24, v6
	v_mul_f32_e32 v24, v144, v162
	v_cvt_pk_bf16_f32 v7, v24, v7
	v_mul_f32_e32 v24, v144, v164
	v_cvt_pk_bf16_f32 v8, v24, v8
	v_mul_f32_e32 v24, v144, v166
	v_cvt_pk_bf16_f32 v9, v24, v9
	s_waitcnt lgkmcnt(1)
	v_mfma_f32_16x16x32_bf16 v[98:101], v[14:17], v[32:35], v[98:101]
	v_mul_f32_e32 v24, v144, v168
	v_cvt_pk_bf16_f32 v2, v24, v2
	v_mul_f32_e32 v24, v144, v170
	v_mfma_f32_16x16x32_bf16 v[32:35], v[6:9], v[32:35], v[82:85]
	v_cvt_pk_bf16_f32 v3, v24, v3
	v_mul_f32_e32 v24, v144, v172
	v_cvt_pk_bf16_f32 v4, v24, v4
	v_mul_f32_e32 v24, v144, v174
	s_waitcnt lgkmcnt(0)
	v_mfma_f32_16x16x32_bf16 v[80:83], v[10:13], v[54:57], v[98:101]
	v_cvt_pk_bf16_f32 v5, v24, v5
	v_lshl_add_u64 v[24:25], v[74:75], 0, s[0:1]
	s_mov_b32 s0, 0x8000
	v_mfma_f32_16x16x32_bf16 v[32:35], v[2:5], v[54:57], v[32:35]
	ds_read_b128 v[54:57], v22 offset:37120
	ds_read_b128 v[98:101], v22 offset:37184
	s_waitcnt lgkmcnt(1)
	v_mfma_f32_16x16x32_bf16 v[94:97], v[14:17], v[54:57], v[94:97]
	v_mfma_f32_16x16x32_bf16 v[54:57], v[6:9], v[54:57], v[70:73]
	s_waitcnt lgkmcnt(0)
	v_mfma_f32_16x16x32_bf16 v[70:73], v[10:13], v[98:101], v[94:97]
	v_mfma_f32_16x16x32_bf16 v[54:57], v[2:5], v[98:101], v[54:57]
	s_nop 3
	ds_read_b128 v[94:97], v23 offset:34816
	ds_read_b128 v[98:101], v23 offset:34880
	s_waitcnt lgkmcnt(1)
	v_mfma_f32_16x16x32_bf16 v[84:87], v[14:17], v[94:97], v[86:89]
	v_mfma_f32_16x16x32_bf16 v[66:69], v[6:9], v[94:97], v[66:69]
	s_waitcnt lgkmcnt(0)
	v_mfma_f32_16x16x32_bf16 v[84:87], v[10:13], v[98:101], v[84:87]
	v_mfma_f32_16x16x32_bf16 v[66:69], v[2:5], v[98:101], v[66:69]
	ds_read_b128 v[94:97], v23 offset:37120
	ds_read_b128 v[98:101], v23 offset:37184
	s_waitcnt lgkmcnt(1)
	v_mfma_f32_16x16x32_bf16 v[76:79], v[14:17], v[94:97], v[76:79]
	v_mfma_f32_16x16x32_bf16 v[62:65], v[6:9], v[94:97], v[62:65]
	s_waitcnt lgkmcnt(0)
	v_mfma_f32_16x16x32_bf16 v[76:79], v[10:13], v[98:101], v[76:79]
	v_mfma_f32_16x16x32_bf16 v[62:65], v[2:5], v[98:101], v[62:65]
	ds_read_b128 v[94:97], v22 offset:44032
	ds_read_b128 v[98:101], v22 offset:44096
	s_waitcnt lgkmcnt(1)
	v_mfma_f32_16x16x32_bf16 v[88:91], v[14:17], v[94:97], v[90:93]
	v_mfma_f32_16x16x32_bf16 v[46:49], v[6:9], v[94:97], v[46:49]
	s_waitcnt lgkmcnt(0)
	v_mfma_f32_16x16x32_bf16 v[88:91], v[10:13], v[98:101], v[88:91]
	v_mfma_f32_16x16x32_bf16 v[46:49], v[2:5], v[98:101], v[46:49]
	ds_read_b128 v[92:95], v22 offset:46336
	ds_read_b128 v[96:99], v22 offset:46400
	v_add_co_u32_e32 v100, vcc, s0, v74
	s_waitcnt lgkmcnt(1)
	v_mfma_f32_16x16x32_bf16 v[58:61], v[14:17], v[92:95], v[58:61]
	v_addc_co_u32_e32 v101, vcc, 0, v75, vcc
	s_mov_b64 s[0:1], 0x8080
	v_mfma_f32_16x16x32_bf16 v[42:45], v[6:9], v[92:95], v[42:45]
	s_waitcnt lgkmcnt(0)
	v_mfma_f32_16x16x32_bf16 v[58:61], v[10:13], v[96:99], v[58:61]
	v_mfma_f32_16x16x32_bf16 v[42:45], v[2:5], v[96:99], v[42:45]
	ds_read_b128 v[92:95], v22 offset:48640
	ds_read_b128 v[96:99], v22 offset:48704
	s_waitcnt lgkmcnt(1)
	v_mfma_f32_16x16x32_bf16 v[50:53], v[14:17], v[92:95], v[50:53]
	v_mfma_f32_16x16x32_bf16 v[36:39], v[6:9], v[92:95], v[38:41]
	s_waitcnt lgkmcnt(0)
	v_mfma_f32_16x16x32_bf16 v[50:53], v[10:13], v[96:99], v[50:53]
	v_mfma_f32_16x16x32_bf16 v[36:39], v[2:5], v[96:99], v[36:39]
	ds_read_b128 v[92:95], v22 offset:50944
	ds_read_b128 v[96:99], v22 offset:51008
	s_waitcnt lgkmcnt(0)
	s_barrier
	v_mfma_f32_16x16x32_bf16 v[14:17], v[14:17], v[92:95], v[28:31]
	v_mfma_f32_16x16x32_bf16 v[6:9], v[6:9], v[92:95], v[18:21]
	s_nop 2
	s_waitcnt vmcnt(3)
	ds_write_b128 v26, v[228:231] offset:34816
	s_waitcnt vmcnt(2)
	ds_write_b128 v26, v[232:235] offset:34832
	v_mfma_f32_16x16x32_bf16 v[10:13], v[10:13], v[96:99], v[14:17]
	s_waitcnt lgkmcnt(0)
	s_barrier
	s_nop 0
	v_sub_u32_e32 v14, 0x100, v143
	v_cvt_f32_i32_e32 v14, v14
	v_sub_u32_e32 v15, 0xf0, v143
	v_cvt_f32_i32_e32 v15, v15
	v_mfma_f32_16x16x32_bf16 v[2:5], v[2:5], v[96:99], v[6:9]
	ds_read_b128 v[28:31], v22 offset:34816
	ds_read_b128 v[96:99], v22 offset:34880
	s_nop 0
	v_mul_f32_e32 v6, v142, v14
	v_exp_f32_e32 v24, v6
	v_mul_f32_e32 v6, v142, v15
	v_exp_f32_e32 v142, v6
	v_mul_f32_e32 v6, v24, v118
	v_mul_f32_e32 v7, v24, v119
	v_cvt_pk_bf16_f32 v6, v6, v7
	v_mul_f32_e32 v7, v24, v120
	v_mul_f32_e32 v8, v24, v121
	v_cvt_pk_bf16_f32 v7, v7, v8
	v_mul_f32_e32 v8, v24, v122
	v_mul_f32_e32 v9, v24, v123
	v_cvt_pk_bf16_f32 v8, v8, v9
	v_mul_f32_e32 v9, v24, v124
	v_mul_f32_e32 v14, v24, v125
	v_cvt_pk_bf16_f32 v9, v9, v14
	v_mul_f32_e32 v14, v24, v126
	v_mul_f32_e32 v15, v24, v127
	v_cvt_pk_bf16_f32 v14, v14, v15
	v_mul_f32_e32 v15, v24, v128
	v_mul_f32_e32 v16, v24, v129
	v_cvt_pk_bf16_f32 v15, v15, v16
	v_mul_f32_e32 v16, v24, v130
	v_mul_f32_e32 v17, v24, v131
	v_cvt_pk_bf16_f32 v16, v16, v17
	v_mul_f32_e32 v17, v24, v132
	v_mul_f32_e32 v18, v24, v133
	v_cvt_pk_bf16_f32 v17, v17, v18
	v_mul_f32_e32 v18, v142, v134
	v_mul_f32_e32 v19, v142, v136
	v_cvt_pk_bf16_f32 v18, v18, v19
	v_mul_f32_e32 v19, v142, v137
	v_mul_f32_e32 v20, v142, v27
	v_cvt_pk_bf16_f32 v19, v19, v20
	v_mul_f32_e32 v20, v142, v138
	v_mul_f32_e32 v21, v142, v139
	v_cvt_pk_bf16_f32 v20, v20, v21
	v_mul_f32_e32 v21, v142, v146
	v_mul_f32_e32 v25, v142, v147
	v_cvt_pk_bf16_f32 v21, v21, v25
	s_waitcnt lgkmcnt(1)
	v_mfma_f32_16x16x32_bf16 v[80:83], v[6:9], v[28:31], v[80:83]
	v_mul_f32_e32 v25, v142, v148
	v_mul_f32_e32 v27, v142, v149
	v_cvt_pk_bf16_f32 v92, v25, v27
	v_mfma_f32_16x16x32_bf16 v[28:31], v[18:21], v[28:31], v[32:35]
	v_mul_f32_e32 v25, v142, v150
	v_mul_f32_e32 v27, v142, v151
	v_cvt_pk_bf16_f32 v93, v25, v27
	v_mul_f32_e32 v25, v142, v135
	v_mul_f32_e32 v27, v142, v152
	v_cvt_pk_bf16_f32 v94, v25, v27
	s_waitcnt lgkmcnt(0)
	v_mfma_f32_16x16x32_bf16 v[32:35], v[14:17], v[96:99], v[80:83]
	v_mul_f32_e32 v25, v142, v153
	v_mul_f32_e32 v27, v142, v154
	v_cvt_pk_bf16_f32 v95, v25, v27
	s_nop 0
	v_mfma_f32_16x16x32_bf16 v[28:31], v[92:95], v[96:99], v[28:31]
	ds_read_b128 v[80:83], v22 offset:37120
	ds_read_b128 v[96:99], v22 offset:37184
	s_waitcnt lgkmcnt(1)
	v_mfma_f32_16x16x32_bf16 v[70:73], v[6:9], v[80:83], v[70:73]
	v_mfma_f32_16x16x32_bf16 v[54:57], v[18:21], v[80:83], v[54:57]
	s_waitcnt lgkmcnt(0)
	v_mfma_f32_16x16x32_bf16 v[70:73], v[14:17], v[96:99], v[70:73]
	v_mfma_f32_16x16x32_bf16 v[54:57], v[92:95], v[96:99], v[54:57]
	ds_read_b128 v[80:83], v23 offset:34816
	ds_read_b128 v[96:99], v23 offset:34880
	s_waitcnt lgkmcnt(1)
	v_mfma_f32_16x16x32_bf16 v[84:87], v[6:9], v[80:83], v[84:87]
	v_mfma_f32_16x16x32_bf16 v[66:69], v[18:21], v[80:83], v[66:69]
	s_waitcnt lgkmcnt(0)
	v_mfma_f32_16x16x32_bf16 v[102:105], v[14:17], v[96:99], v[84:87]
	ds_read_b128 v[80:83], v23 offset:37120
	s_nop 3
	ds_read_b128 v[84:87], v23 offset:37184
	s_waitcnt lgkmcnt(1)
	v_mfma_f32_16x16x32_bf16 v[76:79], v[6:9], v[80:83], v[76:79]
	v_mfma_f32_16x16x32_bf16 v[62:65], v[18:21], v[80:83], v[62:65]
	s_waitcnt lgkmcnt(0)
	v_mfma_f32_16x16x32_bf16 v[76:79], v[14:17], v[84:87], v[76:79]
	v_mfma_f32_16x16x32_bf16 v[62:65], v[92:95], v[84:87], v[62:65]
	ds_read_b128 v[80:83], v22 offset:44032
	ds_read_b128 v[84:87], v22 offset:44096
	s_waitcnt lgkmcnt(1)
	v_mfma_f32_16x16x32_bf16 v[88:91], v[6:9], v[80:83], v[88:91]
	v_mfma_f32_16x16x32_bf16 v[46:49], v[18:21], v[80:83], v[46:49]
	s_waitcnt lgkmcnt(0)
	v_mfma_f32_16x16x32_bf16 v[106:109], v[14:17], v[84:87], v[88:91]
	v_mfma_f32_16x16x32_bf16 v[46:49], v[92:95], v[84:87], v[46:49]
	ds_read_b128 v[80:83], v22 offset:46336
	ds_read_b128 v[84:87], v22 offset:46400
	s_waitcnt lgkmcnt(1)
	v_mfma_f32_16x16x32_bf16 v[58:61], v[6:9], v[80:83], v[58:61]
	v_mfma_f32_16x16x32_bf16 v[40:43], v[18:21], v[80:83], v[42:45]
	s_waitcnt lgkmcnt(0)
	v_mfma_f32_16x16x32_bf16 v[58:61], v[14:17], v[84:87], v[58:61]
	s_nop 0
	v_mul_f32_e32 v44, v142, v168
	v_mul_f32_e32 v45, v142, v169
	v_mfma_f32_16x16x32_bf16 v[40:43], v[92:95], v[84:87], v[40:43]
	ds_read_b128 v[80:83], v22 offset:48640
	ds_read_b128 v[84:87], v22 offset:48704
	s_waitcnt lgkmcnt(1)
	v_mfma_f32_16x16x32_bf16 v[50:53], v[6:9], v[80:83], v[50:53]
	v_mfma_f32_16x16x32_bf16 v[36:39], v[18:21], v[80:83], v[36:39]
	s_waitcnt lgkmcnt(0)
	v_mfma_f32_16x16x32_bf16 v[50:53], v[14:17], v[84:87], v[50:53]
	v_mfma_f32_16x16x32_bf16 v[36:39], v[92:95], v[84:87], v[36:39]
	ds_read_b128 v[80:83], v22 offset:50944
	ds_read_b128 v[84:87], v22 offset:51008
	s_waitcnt lgkmcnt(0)
	s_barrier
	v_mfma_f32_16x16x32_bf16 v[6:9], v[6:9], v[80:83], v[10:13]
	v_mfma_f32_16x16x32_bf16 v[6:9], v[14:17], v[84:87], v[6:9]
	v_lshl_add_u64 v[14:15], v[74:75], 0, s[0:1]
	s_nop 0
	s_nop 0
	s_waitcnt vmcnt(1)
	ds_write_b128 v26, v[236:239] offset:34816
	s_waitcnt vmcnt(0)
	ds_write_b128 v26, v[208:211] offset:34832
	v_mul_f32_e32 v10, v24, v110
	v_mul_f32_e32 v11, v24, v111
	v_cvt_pk_bf16_f32 v10, v10, v11
	v_mul_f32_e32 v11, v24, v112
	v_mul_f32_e32 v12, v24, v113
	v_cvt_pk_bf16_f32 v11, v11, v12
	v_mul_f32_e32 v12, v24, v114
	v_mul_f32_e32 v13, v24, v115
	v_cvt_pk_bf16_f32 v12, v12, v13
	v_mul_f32_e32 v13, v24, v116
	v_mul_f32_e32 v14, v24, v117
	v_cvt_pk_bf16_f32 v13, v13, v14
	v_mul_f32_e32 v14, v24, v141
	v_mul_f32_e32 v15, v24, v145
	v_cvt_pk_bf16_f32 v14, v14, v15
	v_mul_f32_e32 v15, v24, v155
	v_mul_f32_e32 v16, v24, v156
	v_cvt_pk_bf16_f32 v15, v15, v16
	v_mul_f32_e32 v16, v24, v157
	v_mul_f32_e32 v17, v24, v158
	v_mfma_f32_16x16x32_bf16 v[2:5], v[18:21], v[80:83], v[2:5]
	v_cvt_pk_bf16_f32 v16, v16, v17
	v_mul_f32_e32 v17, v24, v159
	v_mul_f32_e32 v18, v24, v160
	v_cvt_pk_bf16_f32 v17, v17, v18
	v_mul_f32_e32 v18, v142, v140
	v_mul_f32_e32 v19, v142, v161
	v_cvt_pk_bf16_f32 v18, v18, v19
	v_mul_f32_e32 v19, v142, v162
	v_mul_f32_e32 v20, v142, v163
	v_cvt_pk_bf16_f32 v19, v19, v20
	v_mul_f32_e32 v20, v142, v164
	v_mul_f32_e32 v21, v142, v165
	v_cvt_pk_bf16_f32 v20, v20, v21
	v_mul_f32_e32 v21, v142, v166
	v_mul_f32_e32 v24, v142, v167
	s_waitcnt lgkmcnt(0)
	s_barrier
	v_cvt_pk_bf16_f32 v21, v21, v24
	ds_read_b128 v[24:27], v22 offset:34816
	ds_read_b128 v[80:83], v22 offset:34880
	s_waitcnt lgkmcnt(1)
	v_mfma_f32_16x16x32_bf16 v[32:35], v[10:13], v[24:27], v[32:35]
	v_cvt_pk_bf16_f32 v110, v44, v45
	v_mul_f32_e32 v44, v142, v170
	v_mul_f32_e32 v45, v142, v171
	v_mfma_f32_16x16x32_bf16 v[24:27], v[18:21], v[24:27], v[28:31]
	v_cvt_pk_bf16_f32 v111, v44, v45
	v_mfma_f32_16x16x32_bf16 v[66:69], v[92:95], v[96:99], v[66:69]
	s_nop 1
	v_mul_f32_e32 v28, v142, v172
	v_mul_f32_e32 v29, v142, v173
	v_cvt_pk_bf16_f32 v112, v28, v29
	v_mul_f32_e32 v28, v142, v174
	v_mul_f32_e32 v29, v142, v175
	v_mfma_f32_16x16x32_bf16 v[2:5], v[92:95], v[84:87], v[2:5]
	v_cvt_pk_bf16_f32 v113, v28, v29
	s_waitcnt lgkmcnt(0)
	v_mfma_f32_16x16x32_bf16 v[98:101], v[14:17], v[80:83], v[32:35]
	v_mfma_f32_16x16x32_bf16 v[82:85], v[110:113], v[80:83], v[24:27]
	s_nop 2
	ds_read_b128 v[24:27], v22 offset:37120
	ds_read_b128 v[28:31], v22 offset:37184
	s_waitcnt lgkmcnt(1)
	v_mfma_f32_16x16x32_bf16 v[32:35], v[10:13], v[24:27], v[70:73]
	v_mfma_f32_16x16x32_bf16 v[24:27], v[18:21], v[24:27], v[54:57]
	s_waitcnt lgkmcnt(0)
	v_mfma_f32_16x16x32_bf16 v[94:97], v[14:17], v[28:31], v[32:35]
	v_mfma_f32_16x16x32_bf16 v[70:73], v[110:113], v[28:31], v[24:27]
	s_nop 4
	ds_read_b128 v[24:27], v23 offset:34816
	ds_read_b128 v[28:31], v23 offset:34880
	s_waitcnt lgkmcnt(1)
	v_mfma_f32_16x16x32_bf16 v[32:35], v[10:13], v[24:27], v[102:105]
	v_mfma_f32_16x16x32_bf16 v[24:27], v[18:21], v[24:27], v[66:69]
	s_waitcnt lgkmcnt(0)
	v_mfma_f32_16x16x32_bf16 v[86:89], v[14:17], v[28:31], v[32:35]
	v_mfma_f32_16x16x32_bf16 v[66:69], v[110:113], v[28:31], v[24:27]
	s_nop 4
	ds_read_b128 v[24:27], v23 offset:37120
	ds_read_b128 v[28:31], v23 offset:37184
	s_waitcnt lgkmcnt(1)
	v_mfma_f32_16x16x32_bf16 v[32:35], v[10:13], v[24:27], v[76:79]
	v_mfma_f32_16x16x32_bf16 v[24:27], v[18:21], v[24:27], v[62:65]
	s_waitcnt lgkmcnt(0)
	v_mfma_f32_16x16x32_bf16 v[78:81], v[14:17], v[28:31], v[32:35]
	v_mfma_f32_16x16x32_bf16 v[62:65], v[110:113], v[28:31], v[24:27]
	s_nop 4
	ds_read_b128 v[24:27], v22 offset:44032
	ds_read_b128 v[28:31], v22 offset:44096
	s_waitcnt lgkmcnt(1)
	v_mfma_f32_16x16x32_bf16 v[32:35], v[10:13], v[24:27], v[106:109]
	v_mfma_f32_16x16x32_bf16 v[24:27], v[18:21], v[24:27], v[46:49]
	s_waitcnt lgkmcnt(0)
	v_mfma_f32_16x16x32_bf16 v[90:93], v[14:17], v[28:31], v[32:35]
	v_mfma_f32_16x16x32_bf16 v[46:49], v[110:113], v[28:31], v[24:27]
	s_nop 4
	ds_read_b128 v[24:27], v22 offset:46336
	ds_read_b128 v[28:31], v22 offset:46400
	s_waitcnt lgkmcnt(1)
	v_mfma_f32_16x16x32_bf16 v[32:35], v[10:13], v[24:27], v[58:61]
	v_mfma_f32_16x16x32_bf16 v[24:27], v[18:21], v[24:27], v[40:43]
	s_waitcnt lgkmcnt(0)
	v_mfma_f32_16x16x32_bf16 v[58:61], v[14:17], v[28:31], v[32:35]
	v_mfma_f32_16x16x32_bf16 v[42:45], v[110:113], v[28:31], v[24:27]
	s_nop 4
	ds_read_b128 v[24:27], v22 offset:48640
	ds_read_b128 v[28:31], v22 offset:48704
	s_waitcnt lgkmcnt(1)
	v_mfma_f32_16x16x32_bf16 v[32:35], v[10:13], v[24:27], v[50:53]
	v_mfma_f32_16x16x32_bf16 v[24:27], v[18:21], v[24:27], v[36:39]
	s_waitcnt lgkmcnt(0)
	v_mfma_f32_16x16x32_bf16 v[50:53], v[14:17], v[28:31], v[32:35]
	v_mfma_f32_16x16x32_bf16 v[38:41], v[110:113], v[28:31], v[24:27]
	s_nop 4
	ds_read_b128 v[24:27], v22 offset:50944
	ds_read_b128 v[28:31], v22 offset:51008
	s_waitcnt lgkmcnt(1)
	v_mfma_f32_16x16x32_bf16 v[6:9], v[10:13], v[24:27], v[6:9]
	v_mfma_f32_16x16x32_bf16 v[2:5], v[18:21], v[24:27], v[2:5]
	s_waitcnt lgkmcnt(0)
	v_mfma_f32_16x16x32_bf16 v[54:57], v[14:17], v[28:31], v[6:9]
	v_mfma_f32_16x16x32_bf16 v[18:21], v[110:113], v[28:31], v[2:5]
